# adds: p[1] background conversion item as one batch of 32 loads
# speedup vs baseline: 1.0158x; 1.0019x over previous
; #define GAS __attribute__((address_space(1)))
; #define NTLOAD(p) __builtin_nontemporal_load(p)
; __device__ __forceinline__ void cv_p_item(unsigned char* ws, const float* p1, int it, int lane) {
;     const GAS f32x4* src = (const GAS f32x4*)p1 + (size_t)it * 2048 + lane; GAS u32x2* dst = (GAS u32x2*)(ws + WS_PB) + (size_t)it * 2048 + lane;
; #pragma unroll 1
;     for (int b = 0; b < 4; ++b) {
;         f32x4 v[8];
; #pragma unroll
;         for (int j = 0; j < 8; ++j) v[j] = NTLOAD(src + b * 512 + j * 64);
; #pragma unroll
;         for (int j = 0; j < 8; ++j) dst[b * 512 + j * 64] = pk4(v[j]);
;     }
; }
.LBB0_937:
	s_mov_b32 s4, 0x2300000
	v_mov_b32_e32 v248, v6
	v_mov_b32_e32 v249, v7
	v_add_co_u32_e32 v246, vcc, 0xfffff000, v248
	s_nop 1
	v_addc_co_u32_e32 v247, vcc, -1, v249, vcc
	global_load_dwordx4 v[12:15], v[246:247], off offset:-3072 nt
	global_load_dwordx4 v[16:19], v[246:247], off offset:-2048 nt
	global_load_dwordx4 v[20:23], v[246:247], off offset:-1024 nt
	global_load_dwordx4 v[24:27], v[248:249], off offset:-4096 nt
	global_load_dwordx4 v[28:31], v[248:249], off offset:-3072 nt
	global_load_dwordx4 v[32:35], v[248:249], off offset:-2048 nt
	global_load_dwordx4 v[114:117], v[248:249], off offset:-1024 nt
	global_load_dwordx4 v[118:121], v[248:249], off nt
	v_add_co_u32_e32 v248, vcc, 0x2000, v248
	s_nop 1
	v_addc_co_u32_e32 v249, vcc, 0, v249, vcc
	v_add_co_u32_e32 v246, vcc, 0xfffff000, v248
	s_nop 1
	v_addc_co_u32_e32 v247, vcc, -1, v249, vcc
	global_load_dwordx4 v[122:125], v[246:247], off offset:-3072 nt
	global_load_dwordx4 v[126:129], v[246:247], off offset:-2048 nt
	global_load_dwordx4 v[130:133], v[246:247], off offset:-1024 nt
	global_load_dwordx4 v[134:137], v[248:249], off offset:-4096 nt
	global_load_dwordx4 v[138:141], v[248:249], off offset:-3072 nt
	global_load_dwordx4 v[142:145], v[248:249], off offset:-2048 nt
	global_load_dwordx4 v[146:149], v[248:249], off offset:-1024 nt
	global_load_dwordx4 v[150:153], v[248:249], off nt
	v_add_co_u32_e32 v248, vcc, 0x2000, v248
	s_nop 1
	v_addc_co_u32_e32 v249, vcc, 0, v249, vcc
	v_add_co_u32_e32 v246, vcc, 0xfffff000, v248
	s_nop 1
	v_addc_co_u32_e32 v247, vcc, -1, v249, vcc
	global_load_dwordx4 v[154:157], v[246:247], off offset:-3072 nt
	global_load_dwordx4 v[158:161], v[246:247], off offset:-2048 nt
	global_load_dwordx4 v[162:165], v[246:247], off offset:-1024 nt
	global_load_dwordx4 v[166:169], v[248:249], off offset:-4096 nt
	global_load_dwordx4 v[170:173], v[248:249], off offset:-3072 nt
	global_load_dwordx4 v[174:177], v[248:249], off offset:-2048 nt
	global_load_dwordx4 v[178:181], v[248:249], off offset:-1024 nt
	global_load_dwordx4 v[182:185], v[248:249], off nt
	v_add_co_u32_e32 v248, vcc, 0x2000, v248
	s_nop 1
	v_addc_co_u32_e32 v249, vcc, 0, v249, vcc
	v_add_co_u32_e32 v246, vcc, 0xfffff000, v248
	s_nop 1
	v_addc_co_u32_e32 v247, vcc, -1, v249, vcc
	global_load_dwordx4 v[186:189], v[246:247], off offset:-3072 nt
	global_load_dwordx4 v[190:193], v[246:247], off offset:-2048 nt
	global_load_dwordx4 v[194:197], v[246:247], off offset:-1024 nt
	global_load_dwordx4 v[198:201], v[248:249], off offset:-4096 nt
	global_load_dwordx4 v[202:205], v[248:249], off offset:-3072 nt
	global_load_dwordx4 v[206:209], v[248:249], off offset:-2048 nt
	global_load_dwordx4 v[210:213], v[248:249], off offset:-1024 nt
	global_load_dwordx4 v[214:217], v[248:249], off nt
	v_lshl_add_u64 v[10:11], v[4:5], 0, s[0:1]
	v_add_co_u32_e32 v10, vcc, s4, v10
	s_add_u32 s0, s0, 0x1000
	s_addc_u32 s1, s1, 0
	v_addc_co_u32_e32 v11, vcc, 0, v11, vcc
	s_waitcnt vmcnt(31)
	v_cvt_pk_bf16_f32 v8, v12, v13
	v_cvt_pk_bf16_f32 v9, v14, v15
	s_nop 0
	global_store_dwordx2 v[10:11], v[8:9], off
	s_waitcnt vmcnt(30)
	v_cvt_pk_bf16_f32 v8, v16, v17
	v_cvt_pk_bf16_f32 v9, v18, v19
	s_nop 0
	global_store_dwordx2 v[10:11], v[8:9], off offset:512
	s_waitcnt vmcnt(29)
	v_cvt_pk_bf16_f32 v8, v20, v21
	v_cvt_pk_bf16_f32 v9, v22, v23
	s_nop 0
	global_store_dwordx2 v[10:11], v[8:9], off offset:1024
	s_waitcnt vmcnt(28)
	v_cvt_pk_bf16_f32 v8, v24, v25
	v_cvt_pk_bf16_f32 v9, v26, v27
	s_nop 0
	global_store_dwordx2 v[10:11], v[8:9], off offset:1536
	s_waitcnt vmcnt(27)
	v_cvt_pk_bf16_f32 v8, v28, v29
	v_cvt_pk_bf16_f32 v9, v30, v31
	s_nop 0
	global_store_dwordx2 v[10:11], v[8:9], off offset:2048
	s_waitcnt vmcnt(26)
	v_cvt_pk_bf16_f32 v8, v32, v33
	v_cvt_pk_bf16_f32 v9, v34, v35
	s_nop 0
	global_store_dwordx2 v[10:11], v[8:9], off offset:2560
	s_waitcnt vmcnt(25)
	v_cvt_pk_bf16_f32 v8, v114, v115
	v_cvt_pk_bf16_f32 v9, v116, v117
	s_nop 0
	global_store_dwordx2 v[10:11], v[8:9], off offset:3072
	s_waitcnt vmcnt(24)
; #define GAS __attribute__((address_space(1)))
; #define NTLOAD(p) __builtin_nontemporal_load(p)
; __device__ __forceinline__ void cv_p_item(unsigned char* ws, const float* p1, int it, int lane) {
;     const GAS f32x4* src = (const GAS f32x4*)p1 + (size_t)it * 2048 + lane; GAS u32x2* dst = (GAS u32x2*)(ws + WS_PB) + (size_t)it * 2048 + lane;
; #pragma unroll 1
;     for (int b = 0; b < 4; ++b) {
;         f32x4 v[8];
; #pragma unroll
;         for (int j = 0; j < 8; ++j) v[j] = NTLOAD(src + b * 512 + j * 64);
; #pragma unroll
;         for (int j = 0; j < 8; ++j) dst[b * 512 + j * 64] = pk4(v[j]);
;     }
; }
	v_cvt_pk_bf16_f32 v8, v118, v119
	v_cvt_pk_bf16_f32 v9, v120, v121
	s_nop 0
	global_store_dwordx2 v[10:11], v[8:9], off offset:3584
	v_lshl_add_u64 v[10:11], v[4:5], 0, s[0:1]
	v_add_co_u32_e32 v10, vcc, s4, v10
	s_add_u32 s0, s0, 0x1000
	s_addc_u32 s1, s1, 0
	v_addc_co_u32_e32 v11, vcc, 0, v11, vcc
	s_waitcnt vmcnt(23)
	v_cvt_pk_bf16_f32 v8, v122, v123
	v_cvt_pk_bf16_f32 v9, v124, v125
	s_nop 0
	global_store_dwordx2 v[10:11], v[8:9], off
	s_waitcnt vmcnt(22)
	v_cvt_pk_bf16_f32 v8, v126, v127
	v_cvt_pk_bf16_f32 v9, v128, v129
	s_nop 0
	global_store_dwordx2 v[10:11], v[8:9], off offset:512
	s_waitcnt vmcnt(21)
	v_cvt_pk_bf16_f32 v8, v130, v131
	v_cvt_pk_bf16_f32 v9, v132, v133
	s_nop 0
	global_store_dwordx2 v[10:11], v[8:9], off offset:1024
	s_waitcnt vmcnt(20)
	v_cvt_pk_bf16_f32 v8, v134, v135
	v_cvt_pk_bf16_f32 v9, v136, v137
	s_nop 0
	global_store_dwordx2 v[10:11], v[8:9], off offset:1536
	s_waitcnt vmcnt(19)
	v_cvt_pk_bf16_f32 v8, v138, v139
	v_cvt_pk_bf16_f32 v9, v140, v141
	s_nop 0
	global_store_dwordx2 v[10:11], v[8:9], off offset:2048
	s_waitcnt vmcnt(18)
	v_cvt_pk_bf16_f32 v8, v142, v143
	v_cvt_pk_bf16_f32 v9, v144, v145
	s_nop 0
	global_store_dwordx2 v[10:11], v[8:9], off offset:2560
	s_waitcnt vmcnt(17)
	v_cvt_pk_bf16_f32 v8, v146, v147
	v_cvt_pk_bf16_f32 v9, v148, v149
	s_nop 0
	global_store_dwordx2 v[10:11], v[8:9], off offset:3072
	s_waitcnt vmcnt(16)
	v_cvt_pk_bf16_f32 v8, v150, v151
	v_cvt_pk_bf16_f32 v9, v152, v153
	s_nop 0
	global_store_dwordx2 v[10:11], v[8:9], off offset:3584
	v_lshl_add_u64 v[10:11], v[4:5], 0, s[0:1]
	v_add_co_u32_e32 v10, vcc, s4, v10
	s_add_u32 s0, s0, 0x1000
	s_addc_u32 s1, s1, 0
	v_addc_co_u32_e32 v11, vcc, 0, v11, vcc
	s_waitcnt vmcnt(15)
	v_cvt_pk_bf16_f32 v8, v154, v155
	v_cvt_pk_bf16_f32 v9, v156, v157
	s_nop 0
	global_store_dwordx2 v[10:11], v[8:9], off
	s_waitcnt vmcnt(14)
	v_cvt_pk_bf16_f32 v8, v158, v159
	v_cvt_pk_bf16_f32 v9, v160, v161
	s_nop 0
	global_store_dwordx2 v[10:11], v[8:9], off offset:512
	s_waitcnt vmcnt(13)
	v_cvt_pk_bf16_f32 v8, v162, v163
	v_cvt_pk_bf16_f32 v9, v164, v165
	s_nop 0
	global_store_dwordx2 v[10:11], v[8:9], off offset:1024
	s_waitcnt vmcnt(12)
	v_cvt_pk_bf16_f32 v8, v166, v167
	v_cvt_pk_bf16_f32 v9, v168, v169
	s_nop 0
	global_store_dwordx2 v[10:11], v[8:9], off offset:1536
	s_waitcnt vmcnt(11)
	v_cvt_pk_bf16_f32 v8, v170, v171
	v_cvt_pk_bf16_f32 v9, v172, v173
	s_nop 0
	global_store_dwordx2 v[10:11], v[8:9], off offset:2048
	s_waitcnt vmcnt(10)
	v_cvt_pk_bf16_f32 v8, v174, v175
	v_cvt_pk_bf16_f32 v9, v176, v177
	s_nop 0
	global_store_dwordx2 v[10:11], v[8:9], off offset:2560
	s_waitcnt vmcnt(9)
	v_cvt_pk_bf16_f32 v8, v178, v179
	v_cvt_pk_bf16_f32 v9, v180, v181
	s_nop 0
	global_store_dwordx2 v[10:11], v[8:9], off offset:3072
	s_waitcnt vmcnt(8)
	v_cvt_pk_bf16_f32 v8, v182, v183
	v_cvt_pk_bf16_f32 v9, v184, v185
	s_nop 0
	global_store_dwordx2 v[10:11], v[8:9], off offset:3584
	v_lshl_add_u64 v[10:11], v[4:5], 0, s[0:1]
	v_add_co_u32_e32 v10, vcc, s4, v10
	s_add_u32 s0, s0, 0x1000
	s_addc_u32 s1, s1, 0
	v_addc_co_u32_e32 v11, vcc, 0, v11, vcc
	s_waitcnt vmcnt(7)
	v_cvt_pk_bf16_f32 v8, v186, v187
	v_cvt_pk_bf16_f32 v9, v188, v189
	s_nop 0
	global_store_dwordx2 v[10:11], v[8:9], off
	s_waitcnt vmcnt(6)
	v_cvt_pk_bf16_f32 v8, v190, v191
	v_cvt_pk_bf16_f32 v9, v192, v193
	s_nop 0
	global_store_dwordx2 v[10:11], v[8:9], off offset:512
	s_waitcnt vmcnt(5)
	v_cvt_pk_bf16_f32 v8, v194, v195
	v_cvt_pk_bf16_f32 v9, v196, v197
	s_nop 0
	global_store_dwordx2 v[10:11], v[8:9], off offset:1024
	s_waitcnt vmcnt(4)
	v_cvt_pk_bf16_f32 v8, v198, v199
	v_cvt_pk_bf16_f32 v9, v200, v201
	s_nop 0
	global_store_dwordx2 v[10:11], v[8:9], off offset:1536
	s_waitcnt vmcnt(3)
	v_cvt_pk_bf16_f32 v8, v202, v203
	v_cvt_pk_bf16_f32 v9, v204, v205
	s_nop 0
	global_store_dwordx2 v[10:11], v[8:9], off offset:2048
	s_waitcnt vmcnt(2)
	v_cvt_pk_bf16_f32 v8, v206, v207
	v_cvt_pk_bf16_f32 v9, v208, v209
	s_nop 0
	global_store_dwordx2 v[10:11], v[8:9], off offset:2560
	s_waitcnt vmcnt(1)
	v_cvt_pk_bf16_f32 v8, v210, v211
	v_cvt_pk_bf16_f32 v9, v212, v213
	s_nop 0
	global_store_dwordx2 v[10:11], v[8:9], off offset:3072
	s_waitcnt vmcnt(0)
	v_cvt_pk_bf16_f32 v8, v214, v215
	v_cvt_pk_bf16_f32 v9, v216, v217
	s_nop 0
	global_store_dwordx2 v[10:11], v[8:9], off offset:3584
